# round-2 tiles of w_o/down split into two 128-row half-units on 64 WGs (skip ai=1 MFMAs+stores), conversion on WGs>=64 with slices 2500/2900
# baseline (speedup 1.0000x reference)
.LBB0_20:
	s_lshl_b32 s81, s96, 3
	s_add_u32 s0, s0, 0x130
	v_readlane_b32 s36, v253, 48
	s_addc_u32 s1, s1, 0
	s_lshl_b32 s3, s96, 1
	v_readlane_b32 s44, v253, 56
	v_readlane_b32 s45, v253, 57
	s_add_u32 s80, s44, 0x300000
	v_writelane_b32 v254, s0, 0
	s_addc_u32 s93, s45, 0
	v_readlane_b32 s4, v253, 16
	v_writelane_b32 v254, s1, 1
	v_readlane_b32 s5, v253, 17
	s_add_u32 s0, s4, 0x5000000
	s_addc_u32 s1, s5, 0
	v_writelane_b32 v254, s0, 2
	v_readlane_b32 s37, v253, 49
	v_readlane_b32 s38, v253, 50
	v_writelane_b32 v254, s1, 3
	s_ashr_i32 s0, s96, 31
	s_lshr_b32 s0, s0, 29
	s_add_i32 s0, s96, s0
	s_ashr_i32 s1, s0, 3
	s_and_b32 s0, s0, -8
	s_sub_i32 s0, s96, s0
	s_cmp_lt_i32 s0, 0
	v_writelane_b32 v254, s1, 4
	s_cselect_b64 s[4:5], -1, 0
	v_writelane_b32 v254, s4, 5
	v_readlane_b32 s39, v253, 51
	v_readlane_b32 s40, v253, 52
	v_writelane_b32 v254, s5, 6
	v_writelane_b32 v254, s0, 7
	s_lshr_b32 s0, s0, 31
	s_cmp_lt_u32 s96, 64
	v_writelane_b32 v254, s0, 8
	s_cselect_b64 s[0:1], -1, 0
	v_writelane_b32 v254, s0, 9
	v_readlane_b32 s41, v253, 53
	v_readlane_b32 s42, v253, 54
	v_writelane_b32 v254, s1, 10
	v_writelane_b32 v254, s3, 11
	s_sub_i32 s0, s3, 0x80
	v_writelane_b32 v254, s0, 12
	s_lshl_b32 s0, s96, 9
	s_cmpk_lt_i32 s96, 0x100
	v_writelane_b32 v254, s0, 13
	s_cselect_b64 s[0:1], -1, 0
	v_readlane_b32 s43, v253, 55
	v_readlane_b32 s46, v253, 58
	v_readlane_b32 s47, v253, 59
	v_readlane_b32 s48, v253, 60
	v_readlane_b32 s49, v253, 61
	v_readlane_b32 s50, v253, 62
	v_readlane_b32 s51, v253, 63
	v_writelane_b32 v254, s0, 14
	v_readlane_b32 s36, v253, 0
	s_ashr_i32 s4, s96, 5
	v_writelane_b32 v254, s1, 15
	s_and_b32 s0, s96, 3
	s_bfe_u32 s1, s96, 0x30002
	v_writelane_b32 v254, s0, 16
	s_lshl_b32 s3, s0, 11
	s_lshl_b32 s0, s1, 21
	v_readlane_b32 s48, v253, 12
	v_writelane_b32 v254, s1, 17
	v_readlane_b32 s49, v253, 13
	s_add_u32 s20, s48, s0
	s_mov_b32 s0, s4
	s_addc_u32 s21, s49, 0
	s_ashr_i32 s5, s4, 31
	v_writelane_b32 v254, s0, 18
	v_readlane_b32 s10, v253, 22
	v_readlane_b32 s11, v253, 23
	v_writelane_b32 v254, s1, 19
	s_lshl_b64 s[0:1], s[4:5], 13
	s_add_u32 s0, s10, s0
	s_addc_u32 s1, s11, s1
	s_add_u32 s0, s0, s3
	s_addc_u32 s1, s1, 0
	s_add_u32 s4, s20, s3
	v_readlane_b32 s8, v253, 20
	s_addc_u32 s5, s21, 0
	v_readlane_b32 s9, v253, 21
	s_add_u32 s8, s0, 0x800000
	s_addc_u32 s9, s1, 0
	v_writelane_b32 v254, s8, 20
	v_readlane_b32 s50, v253, 14
	v_readlane_b32 s51, v253, 15
	v_writelane_b32 v254, s9, 21
	s_add_u32 s8, s4, 0x100000
	v_writelane_b32 v254, s4, 22
	s_addc_u32 s9, s5, 0
	v_readlane_b32 s6, v253, 18
	v_writelane_b32 v254, s5, 23
	v_writelane_b32 v254, s8, 24
	s_add_u32 s4, s0, 0x800080
	v_readlane_b32 s7, v253, 19
	v_writelane_b32 v254, s9, 25
	v_writelane_b32 v254, s0, 26
	s_addc_u32 s5, s1, 0
	v_readlane_b32 s44, v253, 8
	v_writelane_b32 v254, s1, 27
	v_writelane_b32 v254, s4, 28
	s_not_b32 s0, s96
	v_readlane_b32 s45, v253, 9
	v_writelane_b32 v254, s5, 29
	v_writelane_b32 v254, s0, 30
	s_add_u32 s0, s50, 0x20000
	s_addc_u32 s1, s51, 0
	v_writelane_b32 v254, s0, 31
	v_readlane_b32 s42, v253, 6
	v_readlane_b32 s43, v253, 7
	v_writelane_b32 v254, s1, 32
	s_add_u32 s0, s6, 0x2000000
	v_writelane_b32 v254, s0, 33
	s_addc_u32 s0, s7, 0
	v_writelane_b32 v254, s0, 34
	s_and_b32 s0, s96, 7
	s_or_b32 s0, s0, 64
	v_writelane_b32 v254, s0, 35
	s_and_b32 s0, s96, 1
	v_writelane_b32 v254, s0, 36
	s_add_u32 s0, s76, 0x200
	s_addc_u32 s1, s77, 0
	s_add_u32 s44, s76, 0x1000
	s_addc_u32 s45, s77, 0
	s_add_u32 s42, s76, 0x1100
	v_readlane_b32 s16, v253, 28
	s_addc_u32 s43, s77, 0
	v_readlane_b32 s17, v253, 29
	s_add_u32 s16, s76, 0x1200
	v_readlane_b32 s18, v253, 30
	s_addc_u32 s17, s77, 0
	v_readlane_b32 s19, v253, 31
	s_add_u32 s18, s76, 0x1300
	s_addc_u32 s19, s77, 0
	v_writelane_b32 v254, s0, 37
	s_cmp_eq_u32 s2, 15
	v_readlane_b32 s12, v253, 24
	v_writelane_b32 v254, s1, 38
	s_cselect_b64 s[0:1], -1, 0
	v_writelane_b32 v254, s0, 39
	s_cmp_eq_u32 s2, 14
	v_readlane_b32 s13, v253, 25
	v_writelane_b32 v254, s1, 40
	s_cselect_b64 s[0:1], -1, 0
	v_writelane_b32 v254, s0, 41
	s_cmp_eq_u32 s2, 13
	v_readlane_b32 s14, v253, 26
	v_writelane_b32 v254, s1, 42
	s_cselect_b64 s[0:1], -1, 0
	v_writelane_b32 v254, s0, 43
	s_cmp_eq_u32 s2, 12
	v_readlane_b32 s15, v253, 27
	v_writelane_b32 v254, s1, 44
	s_cselect_b64 s[0:1], -1, 0
	v_writelane_b32 v254, s0, 45
	s_cmp_eq_u32 s2, 11
	v_and_b32_e32 v218, 0xff, v193
	v_writelane_b32 v254, s1, 46
	s_cselect_b64 s[0:1], -1, 0
	v_writelane_b32 v254, s0, 47
	s_cmp_eq_u32 s2, 10
	v_mbcnt_lo_u32_b32 v0, -1, 0
	v_writelane_b32 v254, s1, 48
	s_cselect_b64 s[0:1], -1, 0
	v_writelane_b32 v254, s0, 49
	s_cmp_eq_u32 s2, 9
	v_mbcnt_hi_u32_b32 v228, -1, v0
	v_writelane_b32 v254, s1, 50
	s_cselect_b64 s[0:1], -1, 0
	v_writelane_b32 v254, s0, 51
	s_cmp_eq_u32 s2, 8
	v_and_b32_e32 v0, 64, v228
	v_writelane_b32 v254, s1, 52
	s_cselect_b64 s[0:1], -1, 0
	v_writelane_b32 v254, s0, 53
	s_cmp_eq_u32 s2, 7
	v_mov_b32_e32 v185, 0
	v_writelane_b32 v254, s1, 54
	s_cselect_b64 s[0:1], -1, 0
	v_writelane_b32 v254, s0, 55
	s_cmp_eq_u32 s2, 6
	v_mov_b32_e32 v219, 0x358637bd
	v_writelane_b32 v254, s1, 56
	s_cselect_b64 s[0:1], -1, 0
	v_writelane_b32 v254, s0, 57
	s_cmp_eq_u32 s2, 5
	v_mov_b32_e32 v220, 0xbf1f24be
	v_writelane_b32 v254, s1, 58
	s_cselect_b64 s[0:1], -1, 0
	v_writelane_b32 v254, s0, 59
	s_cmp_eq_u32 s2, 4
	v_mov_b32_e32 v221, 0x3e642e9d
	v_writelane_b32 v254, s1, 60
	s_cselect_b64 s[0:1], -1, 0
	v_writelane_b32 v254, s0, 61
	s_cmp_eq_u32 s2, 3
	v_mov_b32_e32 v222, 0x3ecc95a3
	v_writelane_b32 v254, s1, 62
	s_cselect_b64 s[0:1], -1, 0
	v_writelane_b32 v254, s0, 63
	s_cmp_eq_u32 s2, 2
	v_mov_b32_e32 v223, 0x3c0881c4
	v_writelane_b32 v255, s1, 0
	s_cselect_b64 s[0:1], -1, 0
	v_writelane_b32 v255, s0, 1
	s_cmp_eq_u32 s2, 1
	v_mov_b32_e32 v224, 0xbab64f3b
	v_writelane_b32 v255, s1, 2
	s_cselect_b64 s[0:1], -1, 0
	v_writelane_b32 v255, s0, 3
	s_cmp_eq_u32 s2, 0
	v_mov_b32_e32 v225, 0x23800
	v_writelane_b32 v255, s1, 4
	s_cselect_b64 s[0:1], -1, 0
	v_writelane_b32 v255, s0, 5
	v_mov_b32_e32 v227, 0x23804
	v_mov_b32_e32 v250, 1
	v_writelane_b32 v255, s1, 6
	s_lshl_b32 s0, s2, 8
	s_add_u32 s0, s76, s0
	s_addc_u32 s1, s77, 0
	s_add_u32 s2, s0, 0x1400
	s_addc_u32 s3, s1, 0
	v_writelane_b32 v255, s2, 7
	s_add_u32 s0, s0, 0x2400
	s_addc_u32 s1, s1, 0
	v_writelane_b32 v255, s3, 8
	v_writelane_b32 v255, s0, 9
	v_add_u32_e32 v229, 64, v0
	v_xor_b32_e32 v234, 32, v228
	v_writelane_b32 v255, s1, 10
	s_add_u32 s0, s76, 0x3400
	s_addc_u32 s1, s77, 0
	v_writelane_b32 v255, s0, 11
	v_xor_b32_e32 v235, 1, v228
	v_mov_b32_e32 v236, 0x7fc00000
	v_writelane_b32 v255, s1, 12
	s_add_u32 s0, s76, 0x3500
	s_addc_u32 s1, s77, 0
	v_writelane_b32 v255, s0, 13
	v_mov_b32_e32 v238, 0x7f800000
	v_not_b32_e32 v239, 63
	v_writelane_b32 v255, s1, 14
	v_readlane_b32 s0, v253, 32
	v_readlane_b32 s8, v253, 40
	v_readlane_b32 s1, v253, 33
	v_readlane_b32 s9, v253, 41
	s_add_u32 s0, s8, 0x5a000
	s_addc_u32 s1, s9, 0
	v_writelane_b32 v255, s0, 15
	v_readlane_b32 s3, v253, 35
	v_not_b32_e32 v240, 31
	v_writelane_b32 v255, s1, 16
	s_add_u32 s0, s50, 0x20080
	s_addc_u32 s1, s51, 0
	v_writelane_b32 v255, s0, 17
	v_mov_b32_e32 v241, 0xffc00000
	s_movk_i32 s33, 0x3fff
	v_writelane_b32 v255, s1, 18
	s_lshl_b32 s0, s96, 4
	s_addk_i32 s0, 0xee01
	v_writelane_b32 v255, s0, 19
	s_lshl_b32 s0, s96, 6
	v_writelane_b32 v255, s0, 20
	s_lshl_b32 s0, s96, 8
	v_writelane_b32 v255, s0, 21
	v_writelane_b32 v255, s96, 22
	v_writelane_b32 v255, s72, 23
	s_mov_b32 s36, 0x800000
	s_mov_b32 s70, 0xbfb8aa3b
	v_writelane_b32 v255, s73, 24
	v_writelane_b32 v255, s74, 25
	v_writelane_b32 v255, s75, 26
	v_writelane_b32 v255, s76, 27
	v_writelane_b32 v255, s77, 28
	v_writelane_b32 v255, s78, 29
	v_writelane_b32 v255, s79, 30
	v_writelane_b32 v255, s86, 31
	s_mov_b32 s21, 0x7f800000
	s_movk_i32 s97, 0x7fff
	v_writelane_b32 v255, s87, 32
	v_writelane_b32 v255, s81, 33
	v_writelane_b32 v255, s93, 34
	v_writelane_b32 v255, s16, 35
	s_mov_b32 s71, 0x42ce8ed0
	s_mov_b32 s3, 0xc2b17218
	v_writelane_b32 v255, s17, 36
	v_writelane_b32 v255, s18, 37
	s_mov_b32 s89, 0
	s_mov_b64 s[94:95], 0x1000
	v_writelane_b32 v255, s19, 38
	v_writelane_b32 v255, s42, 39
	s_mov_b64 s[24:25], 0x80
	v_readlane_b32 s37, v253, 1
	v_writelane_b32 v255, s43, 40
	v_writelane_b32 v255, s44, 41
	v_readlane_b32 s38, v253, 2
	v_readlane_b32 s39, v253, 3
	v_writelane_b32 v255, s45, 42
	v_readlane_b32 s40, v253, 4
	v_readlane_b32 s41, v253, 5
	v_readlane_b32 s46, v253, 10
	v_readlane_b32 s47, v253, 11
	v_readlane_b32 s2, v253, 34
	v_readlane_b32 s4, v253, 36
	v_readlane_b32 s5, v253, 37
	v_readlane_b32 s6, v253, 38
	v_readlane_b32 s7, v253, 39
	v_readlane_b32 s10, v253, 42
	v_readlane_b32 s11, v253, 43
	v_readlane_b32 s12, v253, 44
	v_readlane_b32 s13, v253, 45
	v_readlane_b32 s14, v253, 46
	v_readlane_b32 s15, v253, 47
	s_branch .LBB0_24

.LBB0_81:
	s_and_b64 vcc, exec, s[0:1]
	s_cbranch_vccz .LBB0_187
	s_cmp_eq_u32 s91, 4
	s_cselect_b64 s[56:57], -1, 0
	s_cmp_lg_u32 s91, 4
	s_mov_b64 s[0:1], -1
	s_cbranch_scc0 .LBB0_100
	s_mov_b32 s100, 0
	s_mov_b32 s101, 0
	s_sub_i32 s0, s84, 32
	s_cmp_lt_u32 s0, 10
	s_cselect_b32 s20, 64, 0x48
	s_waitcnt vmcnt(0)
	v_mov_b32_e32 v6, v193
	s_lshl_b32 s38, s20, 2
	s_cmp_ge_i32 s96, s38
	v_readfirstlane_b32 s33, v6
	s_cbranch_scc1 .LBB0_99
	v_lshlrev_b32_e32 v3, 4, v6
	v_add_u32_e32 v0, 0x2000, v3
	v_ashrrev_i32_e32 v1, 31, v0
	v_lshrrev_b32_e32 v1, 22, v1
	v_add_u32_e32 v1, v0, v1
	v_ashrrev_i32_e32 v1, 10, v1
	v_mul_i32_i24_e32 v2, 0x400, v1
	v_sub_u32_e32 v0, v0, v2
	v_readlane_b32 s4, v253, 16
	v_lshrrev_b32_e32 v2, 4, v0
	v_readlane_b32 s5, v253, 17
	v_bitop3_b32 v2, v2, v0, 32 bitop3:0x6c
	s_bitcmp1_b32 s92, 0
	v_readlane_b32 s4, v254, 2
	v_ashrrev_i32_e32 v0, 31, v2
	s_cselect_b32 s0, 0x2180000, 0
	s_cmp_eq_u32 s91, 5
	v_readlane_b32 s6, v253, 18
	v_readlane_b32 s7, v253, 19
	v_readlane_b32 s8, v253, 20
	v_readlane_b32 s9, v253, 21
	v_readlane_b32 s10, v253, 22
	v_readlane_b32 s11, v253, 23
	v_readlane_b32 s12, v253, 24
	v_readlane_b32 s13, v253, 25
	v_readlane_b32 s14, v253, 26
	v_readlane_b32 s15, v253, 27
	v_readlane_b32 s16, v253, 28
	v_readlane_b32 s17, v253, 29
	v_readlane_b32 s18, v253, 30
	v_readlane_b32 s19, v253, 31
	v_readlane_b32 s5, v254, 3
	v_lshrrev_b32_e32 v0, 26, v0
	s_cselect_b32 s39, s7, s5
	s_cselect_b32 s40, s6, s4
	v_readlane_b32 s4, v253, 0
	v_add_u32_e32 v4, v2, v0
	v_lshlrev_b32_e32 v5, 3, v1
	v_readlane_b32 s10, v253, 6
	v_readlane_b32 s14, v253, 10
	v_ashrrev_i32_e32 v0, 6, v4
	v_and_b32_e32 v5, -16, v5
	s_movk_i32 s1, 0xb00
	v_readlane_b32 s11, v253, 7
	v_readlane_b32 s15, v253, 11
	s_cselect_b32 s22, s10, s14
	v_add_u32_e32 v5, v0, v5
	s_cselect_b32 s26, 0x400, s1
	s_cselect_b32 s1, s11, s15
	s_add_u32 s41, s22, s0
	v_and_b32_e32 v0, 3, v0
	s_mov_b32 s0, 0xffffe0
	v_lshrrev_b32_e32 v7, 2, v5
	v_lshlrev_b32_e32 v8, 1, v5
	v_and_or_b32 v0, v5, s0, v0
	v_and_b32_e32 v7, 4, v7
	v_and_b32_e32 v8, 24, v8
	v_or3_b32 v0, v0, v7, v8
	v_mul_u32_u24_e32 v7, s26, v0
	v_lshlrev_b32_e32 v0, 5, v1
	v_and_b32_e32 v1, 0xc0, v4
	v_sub_u32_e32 v1, v2, v1
	v_ashrrev_i16_sdwa v1, v250, sext(v1) dst_sel:DWORD dst_unused:UNUSED_PAD src0_sel:DWORD src1_sel:BYTE_0
	v_and_b32_e32 v0, 32, v0
	v_bfe_i32 v1, v1, 0, 16
	v_add_u32_e32 v4, v0, v1
	v_mul_lo_u32 v2, v5, s26
	v_add_lshl_u32 v128, v7, v4, 1
	v_add_lshl_u32 v130, v4, v2, 1
	v_bfe_i32 v4, v6, 27, 1
	v_lshrrev_b32_e32 v4, 22, v4
	v_add_u32_e32 v4, v3, v4
	v_and_b32_e32 v4, 0xfffffc00, v4
	v_sub_u32_e32 v3, v3, v4
	v_lshrrev_b32_e32 v4, 4, v3
	v_bitop3_b32 v4, v4, v3, 32 bitop3:0x6c
	v_ashrrev_i32_e32 v3, 31, v3
	v_lshrrev_b32_e32 v3, 26, v3
	v_add_u32_e32 v3, v4, v3
	v_ashrrev_i32_e32 v5, 6, v3
	v_ashrrev_i32_e32 v3, 31, v6
	v_lshrrev_b32_e32 v3, 26, v3
	v_add_u32_e32 v3, v6, v3
	v_readlane_b32 s5, v253, 1
	v_ashrrev_i32_e32 v3, 6, v3
	s_addc_u32 s42, s1, 0
	s_ashr_i32 s1, s33, 6
	v_lshlrev_b32_e32 v7, 3, v3
	s_lshr_b32 s45, s20, 1
	v_readlane_b32 s4, v254, 5
	s_lshl_b32 s43, s26, 9
	s_ashr_i32 s27, s33, 8
	s_lshl_b32 s88, s26, 8
	s_lshl_b32 s44, s1, 10
	v_and_b32_e32 v7, -16, v7
	s_or_b32 s46, s45, 1
	v_readlane_b32 s5, v254, 6
	v_add_u32_e32 v7, v5, v7
	v_and_b32_e32 v8, 3, v5
	s_and_b64 s[22:23], s[4:5], exec
	v_and_or_b32 v8, v7, s0, v8
	s_cselect_b32 s0, s46, s45
	v_readlane_b32 s4, v254, 7
	s_mul_i32 s0, s0, s4
	v_readlane_b32 s4, v254, 4
	s_add_i32 s0, s0, s4
	s_ashr_i32 s22, s0, 31
	s_lshr_b32 s22, s22, 27
	s_add_i32 s22, s0, s22
	s_ashr_i32 s23, s22, 5
	s_lshl_b32 s28, s23, 3
	s_sub_i32 s23, s20, s28
	s_min_i32 s29, s23, 8
	v_mul_i32_i24_e32 v5, 64, v5
	s_sext_i32_i8 s23, s29
	v_lshrrev_b32_e32 v9, 2, v7
	v_lshlrev_b32_e32 v10, 1, v7
	v_sub_u32_e32 v4, v4, v5
	v_mul_lo_u32 v5, v7, s26
	v_cvt_f32_i32_e32 v7, s23
	v_and_b32_e32 v9, 4, v9
	v_and_b32_e32 v10, 24, v10
	v_lshlrev_b32_e32 v3, 5, v3
	v_ashrrev_i16_sdwa v4, v250, sext(v4) dst_sel:DWORD dst_unused:UNUSED_PAD src0_sel:DWORD src1_sel:BYTE_0
	v_or3_b32 v8, v8, v9, v10
	v_and_b32_e32 v3, 32, v3
	v_bfe_i32 v4, v4, 0, 16
	s_andn2_b32 s22, s22, 31
	v_mul_u32_u24_e32 v8, s26, v8
	v_add_u32_e32 v9, v3, v4
	s_sub_i32 s30, s0, s22
	v_add_lshl_u32 v184, v8, v9, 1
	v_add_lshl_u32 v132, v9, v5, 1
	v_cvt_f32_i32_e32 v8, s30
	v_rcp_iflag_f32_e32 v9, v7
	s_xor_b32 s0, s30, s23
	s_ashr_i32 s0, s0, 30
	s_or_b32 s0, s0, 1
	v_mul_f32_e32 v9, v8, v9
	v_trunc_f32_e32 v9, v9
	v_fma_f32 v8, -v9, v7, v8
	v_cvt_i32_f32_e32 v9, v9
	v_cmp_ge_f32_e64 s[22:23], |v8|, |v7|
	s_and_b64 s[22:23], s[22:23], exec
	s_cselect_b32 s0, s0, 0
	v_readfirstlane_b32 s22, v9
	s_add_i32 s0, s22, s0
	s_mul_i32 s22, s0, s29
	s_sub_i32 s22, s30, s22
	s_sext_i32_i8 s22, s22
	s_add_i32 s69, s28, s22
	s_bfe_i64 s[22:23], s[0:1], 0x80000
	s_mul_hi_i32 s23, s22, s43
	s_mul_i32 s22, s22, s43
	s_add_u32 s34, s41, s22
	s_mul_i32 s29, s69, s43
	s_addc_u32 s35, s42, s23
	s_add_i32 s47, s44, 0x10000
	s_add_i32 s48, s44, 0x12000
	s_mul_hi_i32 s28, s69, s43
	s_waitcnt vmcnt(0)
	s_mov_b32 m0, s47
	s_add_u32 s30, s40, s29
	global_load_lds_dwordx4 v184, s[34:35]
	s_mov_b32 m0, s48
	s_addc_u32 s31, s39, s28
	s_add_i32 s49, s44, 0x2000
	global_load_lds_dwordx4 v128, s[34:35]
	s_mov_b32 m0, s44
	s_add_u32 s22, s34, s88
	global_load_lds_dwordx4 v132, s[30:31]
	s_mov_b32 m0, s49
	s_addc_u32 s23, s35, 0
	s_add_i32 s50, s44, 0x14000
	s_add_i32 s51, s44, 0x16000
	global_load_lds_dwordx4 v130, s[30:31]
	s_mov_b32 m0, s50
	s_add_u32 s28, s30, s88
	global_load_lds_dwordx4 v184, s[22:23]
	s_mov_b32 m0, s51
	s_addc_u32 s29, s31, 0
	s_add_i32 s52, s44, 0x4000
	global_load_lds_dwordx4 v128, s[22:23]
	s_mov_b32 m0, s52
	s_add_i32 s53, s44, 0x6000
	global_load_lds_dwordx4 v132, s[28:29]
	s_mov_b32 m0, s53
	v_writelane_b32 v255, s84, 43
	global_load_lds_dwordx4 v130, s[28:29]
	s_nop 0
	v_writelane_b32 v255, s85, 44
	v_writelane_b32 v255, s86, 45
	v_writelane_b32 v255, s87, 46
	s_cmp_lg_u32 s27, 1
	v_readlane_b32 s6, v253, 2
	v_readlane_b32 s7, v253, 3
	v_readlane_b32 s8, v253, 4
	v_readlane_b32 s9, v253, 5
	v_readlane_b32 s12, v253, 8
	v_readlane_b32 s13, v253, 9
	v_readlane_b32 s16, v253, 12
	v_readlane_b32 s17, v253, 13
	v_readlane_b32 s18, v253, 14
	v_readlane_b32 s19, v253, 15
	s_cbranch_scc1 .LBB0_86
	s_barrier

.LBB0_87:
	v_readlane_b32 s0, v254, 0
	v_readlane_b32 s1, v254, 1
	s_load_dword s0, s[0:1], 0x0
	s_add_i32 s64, s64, 1
	s_waitcnt lgkmcnt(0)
	s_mul_i32 s0, s64, s0
	s_add_i32 s0, s0, s96
	s_mov_b32 s101, 0
	s_cmp_gt_u32 s92, 2
	s_cbranch_scc1 .Lpjh_nohalf
	s_cmp_lg_u32 s64, 1
	s_cbranch_scc1 .Lpjh_nohalf
	s_and_b32 s101, s96, 1
	s_add_i32 s101, s101, 1
	s_lshr_b32 s0, s96, 1
	s_add_i32 s0, s0, 0x100
	s_cmp_lt_u32 s96, 64
	s_cselect_b32 s0, s0, 0x120
.Lpjh_nohalf:
	s_cmp_lt_i32 s0, s38
	s_cselect_b64 s[28:29], -1, 0
	s_cmp_ge_i32 s0, s38
	s_cselect_b64 s[22:23], -1, 0
	s_and_b64 vcc, exec, s[22:23]
	s_cbranch_vccnz .LBB0_89
	s_ashr_i32 s1, s0, 31
	s_lshr_b32 s1, s1, 29
	s_add_i32 s1, s0, s1
	s_ashr_i32 s26, s1, 3
	s_and_b32 s1, s1, -8
	s_sub_i32 s0, s0, s1
	s_cmp_lt_i32 s0, 0
	s_cselect_b32 s1, s46, s45
	s_mul_i32 s0, s1, s0
	s_add_i32 s0, s0, s26
	s_ashr_i32 s1, s0, 31
	s_lshr_b32 s1, s1, 27
	s_add_i32 s1, s0, s1
	s_ashr_i32 s26, s1, 5
	s_lshl_b32 s26, s26, 3
	s_sub_i32 s27, s20, s26
	s_min_i32 s27, s27, 8
	s_abs_i32 s36, s27
	v_cvt_f32_u32_e32 v0, s36
	s_sub_i32 s65, 0, s36
	s_andn2_b32 s1, s1, 31
	s_sub_i32 s0, s0, s1
	v_rcp_iflag_f32_e32 v0, v0
	s_abs_i32 s1, s0
	s_xor_b32 s37, s0, s27
	s_ashr_i32 s37, s37, 31
	v_mul_f32_e32 v0, 0x4f7ffffe, v0
	v_cvt_u32_f32_e32 v0, v0
	s_nop 0
	v_readfirstlane_b32 s66, v0
	s_mul_i32 s65, s65, s66
	s_mul_hi_u32 s65, s66, s65
	s_add_i32 s66, s66, s65
	s_mul_hi_u32 s65, s1, s66
	s_mul_i32 s66, s65, s36
	s_sub_i32 s1, s1, s66
	s_add_i32 s67, s65, 1
	s_sub_i32 s66, s1, s36
	s_cmp_ge_u32 s1, s36
	s_cselect_b32 s65, s67, s65
	s_cselect_b32 s1, s66, s1
	s_add_i32 s66, s65, 1
	s_cmp_ge_u32 s1, s36
	s_cselect_b32 s1, s66, s65
	s_xor_b32 s1, s1, s37
	s_sub_i32 s65, s1, s37
	s_mul_i32 s1, s65, s27
	s_sub_i32 s0, s0, s1
	s_add_i32 s68, s0, s26
.LBB0_89:
	v_cndmask_b32_e64 v0, 0, 1, s[28:29]
	v_cmp_ne_u32_e64 s[0:1], 1, v0
	s_andn2_b64 vcc, exec, s[28:29]
	s_mov_b64 s[28:29], s[30:31]
	s_cbranch_vccnz .LBB0_91
	s_mul_i32 s27, s68, s43
	s_mul_hi_i32 s26, s68, s43
	s_add_u32 s28, s40, s27
	s_addc_u32 s29, s39, s26
	s_cmp_eq_u32 s101, 2
	s_cselect_b32 s26, s88, 0
	s_add_u32 s28, s28, s26
	s_addc_u32 s29, s29, 0

.LBB0_93:
	s_add_u32 s30, s30, 0x80
	s_addc_u32 s31, s31, 0
	s_add_u32 s26, s34, 0x100
	v_mov_b32_e32 v0, 0
	s_addc_u32 s27, s35, 0
	s_mov_b32 s34, 0
	v_mov_b32_e32 v1, v0
	v_mov_b32_e32 v2, v0
	v_mov_b32_e32 v3, v0
	v_mov_b32_e32 v4, v0
	v_mov_b32_e32 v5, v0
	v_mov_b32_e32 v6, v0
	v_mov_b32_e32 v7, v0
	v_mov_b32_e32 v8, v0
	v_mov_b32_e32 v9, v0
	v_mov_b32_e32 v10, v0
	v_mov_b32_e32 v11, v0
	v_mov_b32_e32 v12, v0
	v_mov_b32_e32 v13, v0
	v_mov_b32_e32 v14, v0
	v_mov_b32_e32 v15, v0
	v_mov_b32_e32 v16, v0
	v_mov_b32_e32 v17, v0
	v_mov_b32_e32 v18, v0
	v_mov_b32_e32 v19, v0
	v_mov_b32_e32 v20, v0
	v_mov_b32_e32 v21, v0
	v_mov_b32_e32 v22, v0
	v_mov_b32_e32 v23, v0
	v_mov_b32_e32 v24, v0
	v_mov_b32_e32 v25, v0
	v_mov_b32_e32 v26, v0
	v_mov_b32_e32 v27, v0
	v_mov_b32_e32 v28, v0
	v_mov_b32_e32 v29, v0
	v_mov_b32_e32 v30, v0
	v_mov_b32_e32 v31, v0
	v_mov_b32_e32 v32, v0
	v_mov_b32_e32 v33, v0
	v_mov_b32_e32 v34, v0
	v_mov_b32_e32 v35, v0
	v_mov_b32_e32 v36, v0
	v_mov_b32_e32 v37, v0
	v_mov_b32_e32 v38, v0
	v_mov_b32_e32 v39, v0
	v_mov_b32_e32 v40, v0
	v_mov_b32_e32 v41, v0
	v_mov_b32_e32 v42, v0
	v_mov_b32_e32 v43, v0
	v_mov_b32_e32 v44, v0
	v_mov_b32_e32 v45, v0
	v_mov_b32_e32 v46, v0
	v_mov_b32_e32 v47, v0
	v_mov_b32_e32 v48, v0
	v_mov_b32_e32 v49, v0
	v_mov_b32_e32 v50, v0
	v_mov_b32_e32 v51, v0
	v_mov_b32_e32 v52, v0
	v_mov_b32_e32 v53, v0
	v_mov_b32_e32 v54, v0
	v_mov_b32_e32 v55, v0
	v_mov_b32_e32 v56, v0
	v_mov_b32_e32 v57, v0
	v_mov_b32_e32 v58, v0
	v_mov_b32_e32 v59, v0
	v_mov_b32_e32 v60, v0
	v_mov_b32_e32 v61, v0
	v_mov_b32_e32 v62, v0
	v_mov_b32_e32 v63, v0
	v_mov_b32_e32 v64, v0
	v_mov_b32_e32 v65, v0
	v_mov_b32_e32 v66, v0
	v_mov_b32_e32 v67, v0
	v_mov_b32_e32 v68, v0
	v_mov_b32_e32 v69, v0
	v_mov_b32_e32 v70, v0
	v_mov_b32_e32 v71, v0
	v_mov_b32_e32 v72, v0
	v_mov_b32_e32 v73, v0
	v_mov_b32_e32 v74, v0
	v_mov_b32_e32 v75, v0
	v_mov_b32_e32 v76, v0
	v_mov_b32_e32 v77, v0
	v_mov_b32_e32 v78, v0
	v_mov_b32_e32 v79, v0
	v_mov_b32_e32 v80, v0
	v_mov_b32_e32 v81, v0
	v_mov_b32_e32 v82, v0
	v_mov_b32_e32 v83, v0
	v_mov_b32_e32 v84, v0
	v_mov_b32_e32 v85, v0
	v_mov_b32_e32 v86, v0
	v_mov_b32_e32 v87, v0
	v_mov_b32_e32 v88, v0
	v_mov_b32_e32 v89, v0
	v_mov_b32_e32 v90, v0
	v_mov_b32_e32 v91, v0
	v_mov_b32_e32 v92, v0
	v_mov_b32_e32 v93, v0
	v_mov_b32_e32 v94, v0
	v_mov_b32_e32 v95, v0
	v_mov_b32_e32 v96, v0
	v_mov_b32_e32 v97, v0
	v_mov_b32_e32 v98, v0
	v_mov_b32_e32 v99, v0
	v_mov_b32_e32 v100, v0
	v_mov_b32_e32 v101, v0
	v_mov_b32_e32 v102, v0
	v_mov_b32_e32 v103, v0
	v_mov_b32_e32 v104, v0
	v_mov_b32_e32 v105, v0
	v_mov_b32_e32 v106, v0
	v_mov_b32_e32 v107, v0
	v_mov_b32_e32 v108, v0
	v_mov_b32_e32 v109, v0
	v_mov_b32_e32 v110, v0
	v_mov_b32_e32 v111, v0
	v_mov_b32_e32 v112, v0
	v_mov_b32_e32 v113, v0
	v_mov_b32_e32 v114, v0
	v_mov_b32_e32 v115, v0
	v_mov_b32_e32 v116, v0
	v_mov_b32_e32 v117, v0
	v_mov_b32_e32 v118, v0
	v_mov_b32_e32 v119, v0
	v_mov_b32_e32 v120, v0
	v_mov_b32_e32 v121, v0
	v_mov_b32_e32 v122, v0
	v_mov_b32_e32 v123, v0
	v_mov_b32_e32 v124, v0
	v_mov_b32_e32 v125, v0
	v_mov_b32_e32 v126, v0
	v_mov_b32_e32 v127, v0
	s_cmp_lg_u32 s100, 0
	s_cselect_b64 vcc, -1, 0
.LBB0_94:
	v_or_b32_e32 v138, 0x10000, v142
	v_add_u32_e32 v139, 0x10400, v142
	ds_read_b128 v[144:147], v138
	ds_read_b128 v[148:151], v139
	v_add_u32_e32 v138, 0x10800, v142
	s_add_i32 s71, s34, 2
	v_add_u32_e32 v139, 0x10c00, v142
	ds_read_b128 v[152:155], v138
	ds_read_b128 v[156:159], v139
	s_add_u32 s36, s30, 0x80
	s_addc_u32 s35, s31, 0
	s_cmp_eq_u32 s63, s34
	s_cselect_b32 s34, s28, s36
	s_cselect_b32 s35, s29, s35
	s_cselect_b32 s37, s1, s27
	s_cselect_b32 s36, s0, s26
	v_lshl_add_u64 v[138:139], s[30:31], 0, v[134:135]
	s_add_i32 m0, s44, 0xc000
	ds_read_b128 v[160:163], v141
	ds_read_b128 v[164:167], v141 offset:1024
	ds_read_b128 v[168:171], v141 offset:2048
	ds_read_b128 v[172:175], v141 offset:3072
	ds_read_b128 v[176:179], v141 offset:4096
	ds_read_b128 v[180:183], v141 offset:5120
	ds_read_b128 v[186:189], v141 offset:6144
	ds_read_b128 v[194:197], v141 offset:7168
	global_load_lds_dwordx4 v[138:139], off
	v_lshl_add_u64 v[138:139], s[30:31], 0, v[136:137]
	s_add_i32 m0, s44, 0xe000
	s_nop 0
	global_load_lds_dwordx4 v[138:139], off
	s_waitcnt lgkmcnt(8)
	s_barrier
	s_waitcnt lgkmcnt(0)
	s_setprio 1
	s_waitcnt lgkmcnt(0)
	v_mfma_f32_16x16x32_bf16 v[124:127], v[144:147], v[160:163], v[124:127]
	v_mfma_f32_16x16x32_bf16 v[120:123], v[152:155], v[160:163], v[120:123]
	v_mfma_f32_16x16x32_bf16 v[116:119], v[144:147], v[168:171], v[116:119]
	v_mfma_f32_16x16x32_bf16 v[112:115], v[152:155], v[168:171], v[112:115]
	v_mfma_f32_16x16x32_bf16 v[108:111], v[144:147], v[176:179], v[108:111]
	v_mfma_f32_16x16x32_bf16 v[104:107], v[152:155], v[176:179], v[104:107]
	v_mfma_f32_16x16x32_bf16 v[100:103], v[144:147], v[186:189], v[100:103]
	v_mfma_f32_16x16x32_bf16 v[96:99], v[152:155], v[186:189], v[96:99]
	v_mfma_f32_16x16x32_bf16 v[124:127], v[148:151], v[164:167], v[124:127]
	v_mfma_f32_16x16x32_bf16 v[120:123], v[156:159], v[164:167], v[120:123]
	v_mfma_f32_16x16x32_bf16 v[116:119], v[148:151], v[172:175], v[116:119]
	v_mfma_f32_16x16x32_bf16 v[112:115], v[156:159], v[172:175], v[112:115]
	v_mfma_f32_16x16x32_bf16 v[108:111], v[148:151], v[180:183], v[108:111]
	v_mfma_f32_16x16x32_bf16 v[104:107], v[156:159], v[180:183], v[104:107]
	v_mfma_f32_16x16x32_bf16 v[100:103], v[148:151], v[194:197], v[100:103]
	v_mfma_f32_16x16x32_bf16 v[96:99], v[156:159], v[194:197], v[96:99]
	s_setprio 0
	s_barrier
	v_or_b32_e32 v138, 0x14000, v142
	v_add_u32_e32 v139, 0x14400, v142
	ds_read_b128 v[198:201], v138
	ds_read_b128 v[202:205], v139
	v_add_u32_e32 v138, 0x14800, v142
	v_add_u32_e32 v139, 0x14c00, v142
	s_mov_b32 m0, s47
	ds_read_b128 v[206:209], v138
	ds_read_b128 v[210:213], v139
	v_lshl_add_u64 v[138:139], s[36:37], 0, v[184:185]
	global_load_lds_dwordx4 v[138:139], off
	v_lshl_add_u64 v[190:191], s[36:37], 0, v[128:129]
	s_mov_b32 m0, s48
	s_nop 0
	global_load_lds_dwordx4 v[190:191], off
	s_barrier
	s_waitcnt lgkmcnt(0)
	s_setprio 1
	s_waitcnt lgkmcnt(0)
	v_mfma_f32_16x16x32_bf16 v[92:95], v[198:201], v[160:163], v[92:95]
	v_mfma_f32_16x16x32_bf16 v[88:91], v[206:209], v[160:163], v[88:91]
	v_mfma_f32_16x16x32_bf16 v[84:87], v[198:201], v[168:171], v[84:87]
	v_mfma_f32_16x16x32_bf16 v[80:83], v[206:209], v[168:171], v[80:83]
	v_mfma_f32_16x16x32_bf16 v[76:79], v[198:201], v[176:179], v[76:79]
	v_mfma_f32_16x16x32_bf16 v[72:75], v[206:209], v[176:179], v[72:75]
	v_mfma_f32_16x16x32_bf16 v[68:71], v[198:201], v[186:189], v[68:71]
	v_mfma_f32_16x16x32_bf16 v[64:67], v[206:209], v[186:189], v[64:67]
	v_mfma_f32_16x16x32_bf16 v[92:95], v[202:205], v[164:167], v[92:95]
	v_mfma_f32_16x16x32_bf16 v[88:91], v[210:213], v[164:167], v[88:91]
	v_mfma_f32_16x16x32_bf16 v[84:87], v[202:205], v[172:175], v[84:87]
	v_mfma_f32_16x16x32_bf16 v[80:83], v[210:213], v[172:175], v[80:83]
	v_mfma_f32_16x16x32_bf16 v[76:79], v[202:205], v[180:183], v[76:79]
	v_mfma_f32_16x16x32_bf16 v[72:75], v[210:213], v[180:183], v[72:75]
	v_mfma_f32_16x16x32_bf16 v[68:71], v[202:205], v[194:197], v[68:71]
	v_mfma_f32_16x16x32_bf16 v[64:67], v[210:213], v[194:197], v[64:67]
	s_setprio 0
	s_mov_b32 m0, s44
	v_lshl_add_u64 v[214:215], s[34:35], 0, v[132:133]
	s_barrier
	ds_read_b128 v[160:163], v141 offset:16384
	ds_read_b128 v[164:167], v141 offset:17408
	ds_read_b128 v[168:171], v141 offset:18432
	ds_read_b128 v[172:175], v141 offset:19456
	ds_read_b128 v[176:179], v141 offset:20480
	ds_read_b128 v[180:183], v141 offset:21504
	ds_read_b128 v[186:189], v141 offset:22528
	ds_read_b128 v[194:197], v141 offset:23552
	global_load_lds_dwordx4 v[214:215], off
	v_lshl_add_u64 v[216:217], s[34:35], 0, v[130:131]
	s_mov_b32 m0, s49
	s_nop 0
	global_load_lds_dwordx4 v[216:217], off
	s_barrier
	s_waitcnt lgkmcnt(0)
	s_setprio 1
	s_waitcnt lgkmcnt(0)
	s_cbranch_vccnz .Lpjh_s2
	v_mfma_f32_16x16x32_bf16 v[60:63], v[144:147], v[160:163], v[60:63]
	v_mfma_f32_16x16x32_bf16 v[56:59], v[152:155], v[160:163], v[56:59]
	v_mfma_f32_16x16x32_bf16 v[52:55], v[144:147], v[168:171], v[52:55]
	v_mfma_f32_16x16x32_bf16 v[48:51], v[152:155], v[168:171], v[48:51]
	v_mfma_f32_16x16x32_bf16 v[44:47], v[144:147], v[176:179], v[44:47]
	v_mfma_f32_16x16x32_bf16 v[40:43], v[152:155], v[176:179], v[40:43]
	v_mfma_f32_16x16x32_bf16 v[36:39], v[144:147], v[186:189], v[36:39]
	v_mfma_f32_16x16x32_bf16 v[32:35], v[152:155], v[186:189], v[32:35]
	v_mfma_f32_16x16x32_bf16 v[60:63], v[148:151], v[164:167], v[60:63]
	v_mfma_f32_16x16x32_bf16 v[56:59], v[156:159], v[164:167], v[56:59]
	v_mfma_f32_16x16x32_bf16 v[52:55], v[148:151], v[172:175], v[52:55]
	v_mfma_f32_16x16x32_bf16 v[48:51], v[156:159], v[172:175], v[48:51]
	v_mfma_f32_16x16x32_bf16 v[44:47], v[148:151], v[180:183], v[44:47]
	v_mfma_f32_16x16x32_bf16 v[40:43], v[156:159], v[180:183], v[40:43]
	v_mfma_f32_16x16x32_bf16 v[36:39], v[148:151], v[194:197], v[36:39]
	v_mfma_f32_16x16x32_bf16 v[32:35], v[156:159], v[194:197], v[32:35]
.Lpjh_s2:
	s_setprio 0
	s_barrier
	s_add_u32 s36, s36, s88
	s_addc_u32 s37, s37, 0
	s_mov_b32 m0, s50
	v_lshl_add_u64 v[230:231], s[36:37], 0, v[184:185]
	global_load_lds_dwordx4 v[230:231], off
	v_lshl_add_u64 v[232:233], s[36:37], 0, v[128:129]
	s_mov_b32 m0, s51
	s_nop 0
	global_load_lds_dwordx4 v[232:233], off
	s_waitcnt vmcnt(6)
	s_barrier
	s_setprio 1
	s_cbranch_vccnz .Lpjh_s3
	v_mfma_f32_16x16x32_bf16 v[28:31], v[198:201], v[160:163], v[28:31]
	v_mfma_f32_16x16x32_bf16 v[24:27], v[206:209], v[160:163], v[24:27]
	v_mfma_f32_16x16x32_bf16 v[20:23], v[198:201], v[168:171], v[20:23]
	v_mfma_f32_16x16x32_bf16 v[16:19], v[206:209], v[168:171], v[16:19]
	v_mfma_f32_16x16x32_bf16 v[12:15], v[198:201], v[176:179], v[12:15]
	v_mfma_f32_16x16x32_bf16 v[8:11], v[206:209], v[176:179], v[8:11]
	v_mfma_f32_16x16x32_bf16 v[4:7], v[198:201], v[186:189], v[4:7]
	v_mfma_f32_16x16x32_bf16 v[0:3], v[206:209], v[186:189], v[0:3]
	v_mfma_f32_16x16x32_bf16 v[28:31], v[202:205], v[164:167], v[28:31]
	v_mfma_f32_16x16x32_bf16 v[24:27], v[210:213], v[164:167], v[24:27]
	v_mfma_f32_16x16x32_bf16 v[20:23], v[202:205], v[172:175], v[20:23]
	v_mfma_f32_16x16x32_bf16 v[16:19], v[210:213], v[172:175], v[16:19]
	v_mfma_f32_16x16x32_bf16 v[12:15], v[202:205], v[180:183], v[12:15]
	v_mfma_f32_16x16x32_bf16 v[8:11], v[210:213], v[180:183], v[8:11]
	v_mfma_f32_16x16x32_bf16 v[4:7], v[202:205], v[194:197], v[4:7]
	v_mfma_f32_16x16x32_bf16 v[0:3], v[210:213], v[194:197], v[0:3]
.Lpjh_s3:
	s_setprio 0
	v_or_b32_e32 v144, 0x18000, v142
	v_add_u32_e32 v148, 0x18400, v142
	v_add_u32_e32 v152, 0x18800, v142
	v_add_u32_e32 v156, 0x18c00, v142
	s_barrier
	ds_read_b128 v[144:147], v144
	ds_read_b128 v[148:151], v148
	ds_read_b128 v[152:155], v152
	ds_read_b128 v[156:159], v156
	s_add_u32 s34, s34, s88
	s_addc_u32 s35, s35, 0
	s_mov_b32 m0, s52
	v_lshl_add_u64 v[198:199], s[34:35], 0, v[132:133]
	ds_read_b128 v[160:163], v141 offset:32768
	ds_read_b128 v[164:167], v141 offset:33792
	ds_read_b128 v[168:171], v141 offset:34816
	ds_read_b128 v[172:175], v141 offset:35840
	ds_read_b128 v[176:179], v141 offset:36864
	ds_read_b128 v[180:183], v141 offset:37888
	ds_read_b128 v[186:189], v141 offset:38912
	ds_read_b128 v[194:197], v141 offset:39936
	global_load_lds_dwordx4 v[198:199], off
	v_lshl_add_u64 v[198:199], s[34:35], 0, v[130:131]
	s_mov_b32 m0, s53
	s_nop 0
	global_load_lds_dwordx4 v[198:199], off
	s_waitcnt lgkmcnt(8)
	s_barrier
	s_waitcnt lgkmcnt(0)
	s_setprio 1
	s_waitcnt lgkmcnt(0)
	v_mfma_f32_16x16x32_bf16 v[124:127], v[144:147], v[160:163], v[124:127]
	v_mfma_f32_16x16x32_bf16 v[120:123], v[152:155], v[160:163], v[120:123]
	v_mfma_f32_16x16x32_bf16 v[116:119], v[144:147], v[168:171], v[116:119]
	v_mfma_f32_16x16x32_bf16 v[112:115], v[152:155], v[168:171], v[112:115]
	v_mfma_f32_16x16x32_bf16 v[108:111], v[144:147], v[176:179], v[108:111]
	v_mfma_f32_16x16x32_bf16 v[104:107], v[152:155], v[176:179], v[104:107]
	v_mfma_f32_16x16x32_bf16 v[100:103], v[144:147], v[186:189], v[100:103]
	v_mfma_f32_16x16x32_bf16 v[96:99], v[152:155], v[186:189], v[96:99]
	v_mfma_f32_16x16x32_bf16 v[124:127], v[148:151], v[164:167], v[124:127]
	v_mfma_f32_16x16x32_bf16 v[120:123], v[156:159], v[164:167], v[120:123]
	v_mfma_f32_16x16x32_bf16 v[116:119], v[148:151], v[172:175], v[116:119]
	v_mfma_f32_16x16x32_bf16 v[112:115], v[156:159], v[172:175], v[112:115]
	v_mfma_f32_16x16x32_bf16 v[108:111], v[148:151], v[180:183], v[108:111]
	v_mfma_f32_16x16x32_bf16 v[104:107], v[156:159], v[180:183], v[104:107]
	v_mfma_f32_16x16x32_bf16 v[100:103], v[148:151], v[194:197], v[100:103]
	v_mfma_f32_16x16x32_bf16 v[96:99], v[156:159], v[194:197], v[96:99]
	s_setprio 0
	s_barrier
	v_or_b32_e32 v192, 0x1c000, v142
	v_add_u32_e32 v202, 0x1c400, v142
	s_mov_b32 m0, s55
	ds_read_b128 v[198:201], v192
	ds_read_b128 v[202:205], v202
	v_add_u32_e32 v192, 0x1c800, v142
	v_add_u32_e32 v210, 0x1cc00, v142
	v_lshl_add_u64 v[138:139], v[138:139], 0, s[24:25]
	ds_read_b128 v[206:209], v192
	ds_read_b128 v[210:213], v210
	global_load_lds_dwordx4 v[138:139], off
	v_lshl_add_u64 v[138:139], v[190:191], 0, s[24:25]
	s_mov_b32 m0, s58
	s_nop 0
	global_load_lds_dwordx4 v[138:139], off
	s_barrier
	s_waitcnt lgkmcnt(0)
	s_setprio 1
	s_waitcnt lgkmcnt(0)
	v_mfma_f32_16x16x32_bf16 v[92:95], v[198:201], v[160:163], v[92:95]
	v_mfma_f32_16x16x32_bf16 v[88:91], v[206:209], v[160:163], v[88:91]
	v_mfma_f32_16x16x32_bf16 v[84:87], v[198:201], v[168:171], v[84:87]
	v_mfma_f32_16x16x32_bf16 v[80:83], v[206:209], v[168:171], v[80:83]
	v_mfma_f32_16x16x32_bf16 v[76:79], v[198:201], v[176:179], v[76:79]
	v_mfma_f32_16x16x32_bf16 v[72:75], v[206:209], v[176:179], v[72:75]
	v_mfma_f32_16x16x32_bf16 v[68:71], v[198:201], v[186:189], v[68:71]
	v_mfma_f32_16x16x32_bf16 v[64:67], v[206:209], v[186:189], v[64:67]
	v_mfma_f32_16x16x32_bf16 v[92:95], v[202:205], v[164:167], v[92:95]
	v_mfma_f32_16x16x32_bf16 v[88:91], v[210:213], v[164:167], v[88:91]
	v_mfma_f32_16x16x32_bf16 v[84:87], v[202:205], v[172:175], v[84:87]
	v_mfma_f32_16x16x32_bf16 v[80:83], v[210:213], v[172:175], v[80:83]
	v_mfma_f32_16x16x32_bf16 v[76:79], v[202:205], v[180:183], v[76:79]
	v_mfma_f32_16x16x32_bf16 v[72:75], v[210:213], v[180:183], v[72:75]
	v_mfma_f32_16x16x32_bf16 v[68:71], v[202:205], v[194:197], v[68:71]
	v_mfma_f32_16x16x32_bf16 v[64:67], v[210:213], v[194:197], v[64:67]
	s_setprio 0
	s_mov_b32 m0, s59
	v_lshl_add_u64 v[138:139], v[214:215], 0, s[24:25]
	s_barrier
	ds_read_b128 v[160:163], v141 offset:49152
	ds_read_b128 v[164:167], v141 offset:50176
	ds_read_b128 v[168:171], v141 offset:51200
	ds_read_b128 v[172:175], v141 offset:52224
	ds_read_b128 v[176:179], v141 offset:53248
	ds_read_b128 v[180:183], v141 offset:54272
	ds_read_b128 v[186:189], v141 offset:55296
	ds_read_b128 v[194:197], v141 offset:56320
	global_load_lds_dwordx4 v[138:139], off
	v_lshl_add_u64 v[138:139], v[216:217], 0, s[24:25]
	s_mov_b32 m0, s60
	s_nop 0
	global_load_lds_dwordx4 v[138:139], off
	s_barrier
	s_waitcnt lgkmcnt(0)
	s_setprio 1
	s_waitcnt lgkmcnt(0)
	s_cbranch_vccnz .Lpjh_s6
	v_mfma_f32_16x16x32_bf16 v[60:63], v[144:147], v[160:163], v[60:63]
	v_mfma_f32_16x16x32_bf16 v[56:59], v[152:155], v[160:163], v[56:59]
	v_mfma_f32_16x16x32_bf16 v[52:55], v[144:147], v[168:171], v[52:55]
	v_mfma_f32_16x16x32_bf16 v[48:51], v[152:155], v[168:171], v[48:51]
	v_mfma_f32_16x16x32_bf16 v[44:47], v[144:147], v[176:179], v[44:47]
	v_mfma_f32_16x16x32_bf16 v[40:43], v[152:155], v[176:179], v[40:43]
	v_mfma_f32_16x16x32_bf16 v[36:39], v[144:147], v[186:189], v[36:39]
	v_mfma_f32_16x16x32_bf16 v[32:35], v[152:155], v[186:189], v[32:35]
	v_mfma_f32_16x16x32_bf16 v[60:63], v[148:151], v[164:167], v[60:63]
	v_mfma_f32_16x16x32_bf16 v[56:59], v[156:159], v[164:167], v[56:59]
	v_mfma_f32_16x16x32_bf16 v[52:55], v[148:151], v[172:175], v[52:55]
	v_mfma_f32_16x16x32_bf16 v[48:51], v[156:159], v[172:175], v[48:51]
	v_mfma_f32_16x16x32_bf16 v[44:47], v[148:151], v[180:183], v[44:47]
	v_mfma_f32_16x16x32_bf16 v[40:43], v[156:159], v[180:183], v[40:43]
	v_mfma_f32_16x16x32_bf16 v[36:39], v[148:151], v[194:197], v[36:39]
	v_mfma_f32_16x16x32_bf16 v[32:35], v[156:159], v[194:197], v[32:35]
.Lpjh_s6:
	s_setprio 0
	s_barrier
	s_mov_b32 m0, s61
	v_lshl_add_u64 v[138:139], v[230:231], 0, s[24:25]
	global_load_lds_dwordx4 v[138:139], off
	v_lshl_add_u64 v[138:139], v[232:233], 0, s[24:25]
	s_mov_b32 m0, s62
	s_nop 0
	global_load_lds_dwordx4 v[138:139], off
	s_waitcnt vmcnt(6)
	s_barrier
	s_setprio 1
	s_cbranch_vccnz .Lpjh_s7
	v_mfma_f32_16x16x32_bf16 v[28:31], v[198:201], v[160:163], v[28:31]
	v_mfma_f32_16x16x32_bf16 v[24:27], v[206:209], v[160:163], v[24:27]
	v_mfma_f32_16x16x32_bf16 v[20:23], v[198:201], v[168:171], v[20:23]
	v_mfma_f32_16x16x32_bf16 v[16:19], v[206:209], v[168:171], v[16:19]
	v_mfma_f32_16x16x32_bf16 v[12:15], v[198:201], v[176:179], v[12:15]
	v_mfma_f32_16x16x32_bf16 v[8:11], v[206:209], v[176:179], v[8:11]
	v_mfma_f32_16x16x32_bf16 v[4:7], v[198:201], v[186:189], v[4:7]
	v_mfma_f32_16x16x32_bf16 v[0:3], v[206:209], v[186:189], v[0:3]
	v_mfma_f32_16x16x32_bf16 v[28:31], v[202:205], v[164:167], v[28:31]
	v_mfma_f32_16x16x32_bf16 v[24:27], v[210:213], v[164:167], v[24:27]
	v_mfma_f32_16x16x32_bf16 v[20:23], v[202:205], v[172:175], v[20:23]
	v_mfma_f32_16x16x32_bf16 v[16:19], v[210:213], v[172:175], v[16:19]
	v_mfma_f32_16x16x32_bf16 v[12:15], v[202:205], v[180:183], v[12:15]
	v_mfma_f32_16x16x32_bf16 v[8:11], v[210:213], v[180:183], v[8:11]
	v_mfma_f32_16x16x32_bf16 v[4:7], v[202:205], v[194:197], v[4:7]
	v_mfma_f32_16x16x32_bf16 v[0:3], v[210:213], v[194:197], v[0:3]
.Lpjh_s7:
	s_setprio 0
	s_add_u32 s30, s30, 0x100
	s_addc_u32 s31, s31, 0
	s_add_u32 s26, s26, 0x100
	s_addc_u32 s27, s27, 0
	s_cmp_ge_u32 s71, s54
	s_mov_b32 s34, s71
	s_barrier
	s_cbranch_scc0 .LBB0_94
	v_lshl_add_u32 v138, s69, 8, v140
	s_cmp_eq_u32 s100, 2
	s_cselect_b32 vcc_lo, 0x80, 0
	s_nop 0
	v_add_u32_e32 v138, vcc_lo, v138
	v_lshl_or_b32 v144, s70, 8, v143
	v_ashrrev_i32_e32 v139, 31, v138
	v_readlane_b32 s4, v253, 16
	v_ashrrev_i32_e32 v145, 31, v144
	v_cvt_pk_bf16_f32 v124, v124, v125
	v_cvt_pk_bf16_f32 v125, v126, v127
	v_cvt_pk_bf16_f32 v126, v120, v121
	v_lshlrev_b64 v[120:121], 11, v[138:139]
	v_readlane_b32 s5, v253, 17
	v_cvt_pk_bf16_f32 v127, v122, v123
	v_lshlrev_b64 v[122:123], 1, v[144:145]
	v_cvt_pk_bf16_f32 v116, v116, v117
	v_cvt_pk_bf16_f32 v117, v118, v119
	v_cvt_pk_bf16_f32 v119, v114, v115
	s_nop 0
	v_lshl_add_u64 v[120:121], s[4:5], 0, v[120:121]
	v_lshl_add_u64 v[120:121], v[120:121], 0, v[122:123]
	global_store_dwordx4 v[120:121], v[124:127], off
	v_or_b32_e32 v114, 32, v138
	v_cvt_pk_bf16_f32 v108, v108, v109
	v_cvt_pk_bf16_f32 v109, v110, v111
	v_cvt_pk_bf16_f32 v111, v106, v107
	v_or_b32_e32 v106, 48, v138
	v_or_b32_e32 v124, 16, v138
	v_cvt_pk_bf16_f32 v68, v68, v69
	v_cvt_pk_bf16_f32 v69, v70, v71
	v_cvt_pk_bf16_f32 v70, v64, v65
	v_add_u32_e32 v64, 0x80, v138
	v_cvt_pk_bf16_f32 v60, v60, v61
	v_cvt_pk_bf16_f32 v61, v62, v63
	v_cvt_pk_bf16_f32 v63, v58, v59
	v_add_u32_e32 v58, 0x90, v138
	v_cvt_pk_bf16_f32 v52, v52, v53
	v_cvt_pk_bf16_f32 v53, v54, v55
	v_cvt_pk_bf16_f32 v55, v50, v51
	v_add_u32_e32 v50, 0xa0, v138
	v_cvt_pk_bf16_f32 v44, v44, v45
	v_cvt_pk_bf16_f32 v45, v46, v47
	v_cvt_pk_bf16_f32 v47, v42, v43
	v_add_u32_e32 v42, 0xb0, v138
	v_ashrrev_i32_e32 v125, 31, v124
	v_ashrrev_i32_e32 v115, 31, v114
	v_ashrrev_i32_e32 v107, 31, v106
	v_ashrrev_i32_e32 v65, 31, v64
	v_ashrrev_i32_e32 v59, 31, v58
	v_ashrrev_i32_e32 v51, 31, v50
	v_ashrrev_i32_e32 v43, 31, v42
	v_cvt_pk_bf16_f32 v118, v112, v113
	v_lshlrev_b64 v[112:113], 11, v[124:125]
	v_cvt_pk_bf16_f32 v110, v104, v105
	v_lshlrev_b64 v[104:105], 11, v[114:115]
	v_cvt_pk_bf16_f32 v100, v100, v101
	v_cvt_pk_bf16_f32 v101, v102, v103
	v_cvt_pk_bf16_f32 v102, v96, v97
	v_lshlrev_b64 v[96:97], 11, v[106:107]
	v_cvt_pk_bf16_f32 v62, v56, v57
	v_lshlrev_b64 v[56:57], 11, v[64:65]
	v_cvt_pk_bf16_f32 v54, v48, v49
	v_lshlrev_b64 v[48:49], 11, v[58:59]
	v_cvt_pk_bf16_f32 v46, v40, v41
	v_lshlrev_b64 v[40:41], 11, v[50:51]
	v_cvt_pk_bf16_f32 v36, v36, v37
	v_cvt_pk_bf16_f32 v37, v38, v39
	v_cvt_pk_bf16_f32 v38, v32, v33
	v_lshlrev_b64 v[32:33], 11, v[42:43]
	v_lshl_add_u64 v[112:113], s[4:5], 0, v[112:113]
	v_lshl_add_u64 v[104:105], s[4:5], 0, v[104:105]
	v_lshl_add_u64 v[96:97], s[4:5], 0, v[96:97]
	v_lshl_add_u64 v[56:57], s[4:5], 0, v[56:57]
	v_lshl_add_u64 v[48:49], s[4:5], 0, v[48:49]
	v_lshl_add_u64 v[40:41], s[4:5], 0, v[40:41]
	v_lshl_add_u64 v[32:33], s[4:5], 0, v[32:33]
	v_lshl_add_u64 v[112:113], v[112:113], 0, v[122:123]
	v_lshl_add_u64 v[104:105], v[104:105], 0, v[122:123]
	v_lshl_add_u64 v[96:97], v[96:97], 0, v[122:123]
	v_lshl_add_u64 v[56:57], v[56:57], 0, v[122:123]
	v_lshl_add_u64 v[48:49], v[48:49], 0, v[122:123]
	v_lshl_add_u64 v[40:41], v[40:41], 0, v[122:123]
	v_lshl_add_u64 v[32:33], v[32:33], 0, v[122:123]
	s_and_b64 vcc, exec, s[22:23]
	s_mov_b32 s70, s65
	s_mov_b32 s69, s68
	s_mov_b64 s[34:35], s[0:1]
	s_mov_b64 s[30:31], s[28:29]
	s_mov_b32 s71, 0x42ce8ed0
	v_readlane_b32 s6, v253, 18
	v_readlane_b32 s7, v253, 19
	v_readlane_b32 s8, v253, 20
	v_readlane_b32 s9, v253, 21
	v_readlane_b32 s10, v253, 22
	v_readlane_b32 s11, v253, 23
	v_readlane_b32 s12, v253, 24
	v_readlane_b32 s13, v253, 25
	v_readlane_b32 s14, v253, 26
	v_readlane_b32 s15, v253, 27
	v_readlane_b32 s16, v253, 28
	v_readlane_b32 s17, v253, 29
	v_readlane_b32 s18, v253, 30
	v_readlane_b32 s19, v253, 31
	global_store_dwordx4 v[112:113], v[116:119], off
	global_store_dwordx4 v[104:105], v[108:111], off
	v_cvt_pk_bf16_f32 v103, v98, v99
	global_store_dwordx4 v[96:97], v[100:103], off
	v_cvt_pk_bf16_f32 v92, v92, v93
	v_cvt_pk_bf16_f32 v93, v94, v95
	v_cvt_pk_bf16_f32 v94, v88, v89
	v_cvt_pk_bf16_f32 v95, v90, v91
	global_store_dwordx4 v[120:121], v[92:95], off offset:256
	v_cvt_pk_bf16_f32 v84, v84, v85
	v_cvt_pk_bf16_f32 v85, v86, v87
	v_cvt_pk_bf16_f32 v86, v80, v81
	v_cvt_pk_bf16_f32 v87, v82, v83
	global_store_dwordx4 v[112:113], v[84:87], off offset:256
	v_cvt_pk_bf16_f32 v76, v76, v77
	v_cvt_pk_bf16_f32 v77, v78, v79
	v_cvt_pk_bf16_f32 v78, v72, v73
	v_cvt_pk_bf16_f32 v79, v74, v75
	global_store_dwordx4 v[104:105], v[76:79], off offset:256
	v_cvt_pk_bf16_f32 v71, v66, v67
	global_store_dwordx4 v[96:97], v[68:71], off offset:256
	s_cmp_lg_u32 s100, 0
	s_cbranch_scc1 .Lpjh_nost
	global_store_dwordx4 v[56:57], v[60:63], off
	global_store_dwordx4 v[48:49], v[52:55], off
	global_store_dwordx4 v[40:41], v[44:47], off
	v_cvt_pk_bf16_f32 v39, v34, v35
	global_store_dwordx4 v[32:33], v[36:39], off
	v_cvt_pk_bf16_f32 v28, v28, v29
	v_cvt_pk_bf16_f32 v29, v30, v31
	v_cvt_pk_bf16_f32 v30, v24, v25
	v_cvt_pk_bf16_f32 v31, v26, v27
	global_store_dwordx4 v[56:57], v[28:31], off offset:256
	v_cvt_pk_bf16_f32 v20, v20, v21
	v_cvt_pk_bf16_f32 v21, v22, v23
	v_cvt_pk_bf16_f32 v22, v16, v17
	v_cvt_pk_bf16_f32 v23, v18, v19
	global_store_dwordx4 v[48:49], v[20:23], off offset:256
	v_cvt_pk_bf16_f32 v12, v12, v13
	v_cvt_pk_bf16_f32 v13, v14, v15
	v_cvt_pk_bf16_f32 v14, v8, v9
	v_cvt_pk_bf16_f32 v15, v10, v11
	global_store_dwordx4 v[40:41], v[12:15], off offset:256
	v_cvt_pk_bf16_f32 v4, v4, v5
	v_cvt_pk_bf16_f32 v5, v6, v7
	v_cvt_pk_bf16_f32 v6, v0, v1
	v_cvt_pk_bf16_f32 v7, v2, v3
	global_store_dwordx4 v[32:33], v[4:7], off offset:256
.Lpjh_nost:
	s_mov_b32 s100, s101
	s_cbranch_vccz .LBB0_87
	s_waitcnt vmcnt(0)
	s_cmpk_gt_u32 s33, 0xff
	s_mov_b32 s70, 0xbfb8aa3b
	s_cbranch_scc1 .LBB0_98
	s_barrier

.LBB0_149:
	s_cmp_gt_i32 s84, 31
	v_readlane_b32 s4, v254, 9
	s_cselect_b64 s[0:1], -1, 0
	v_readlane_b32 s5, v254, 10
	s_or_b64 s[0:1], s[0:1], s[4:5]
	s_and_b64 vcc, exec, s[0:1]
	s_cbranch_vccnz .LBB0_187
	s_cmp_eq_u32 s91, 5
	s_movk_i32 s0, 0x9c4
	s_cselect_b32 s20, s0, 0xb54
	s_movk_i32 s0, 0x1080
	v_readfirstlane_b32 s22, v193
	s_cselect_b32 s23, 0xb54, s0
	s_and_b64 s[0:1], s[56:57], exec
	s_cselect_b32 s26, 0, s20
	s_lshr_b32 s22, s22, 8
	s_and_b64 s[0:1], s[56:57], exec
	v_readlane_b32 s0, v254, 12
	s_cselect_b32 s20, 0x9c4, s23
	s_add_i32 s0, s0, s26
	s_add_i32 s50, s0, s22
	s_waitcnt vmcnt(0)
	v_mov_b32_e32 v1, v218
	s_cmp_ge_i32 s50, s20
	s_waitcnt vmcnt(0) lgkmcnt(0)
	s_barrier
	s_cbranch_scc1 .LBB0_187
	v_readlane_b32 s0, v254, 0
	v_readlane_b32 s1, v254, 1
	s_load_dword s0, s[0:1], 0x0
	s_add_i32 s28, s92, 1
	v_readlane_b32 s52, v253, 0
	v_readlane_b32 s54, v253, 2
	v_readlane_b32 s55, v253, 3
	s_waitcnt lgkmcnt(0)
	s_lshl_b32 s0, s0, 1
	s_sub_i32 s51, s0, 0x80
	s_bitcmp1_b32 s28, 0
	s_cselect_b32 s0, 0x2180000, 0
	s_add_u32 s38, s54, s0
	v_readlane_b32 s56, v253, 4
	s_addc_u32 s39, s55, 0
	v_readlane_b32 s57, v253, 5
	s_add_u32 s40, s56, s0
	v_readlane_b32 s58, v253, 6
	s_addc_u32 s41, s57, 0
	v_cvt_f32_i32_e32 v7, v1
	v_readlane_b32 s59, v253, 7
	s_add_u32 s42, s58, s0
	v_readlane_b32 s60, v253, 8
	s_addc_u32 s43, s59, 0
	v_readlane_b32 s61, v253, 9
	s_add_u32 s44, s60, s0
	v_readlane_b32 s62, v253, 10
	s_addc_u32 s45, s61, 0
	v_mul_f32_e32 v7, 0x3d000000, v7
	v_readlane_b32 s63, v253, 11
	s_add_u32 s46, s62, s0
	v_readlane_b32 s4, v253, 32
	v_mul_f32_e64 v8, |v7|, 0.5
	s_mul_i32 s22, s28, 0x1900000
	s_addc_u32 s47, s63, 0
	s_ashr_i32 s29, s28, 31
	v_readlane_b32 s18, v253, 46
	v_fract_f32_e32 v9, v8
	s_mul_hi_i32 s1, s28, 0x1900000
	v_readlane_b32 s19, v253, 47
	s_add_u32 s48, s18, s22
	v_add_f32_e32 v9, v9, v9
	v_cmp_neq_f32_e32 vcc, s21, v8
	s_addc_u32 s49, s19, s1
	v_cmp_gt_f32_e64 s[0:1], |v7|, 1.0
	v_cndmask_b32_e32 v8, 0, v9, vcc
	v_readlane_b32 s53, v253, 1
	v_cndmask_b32_e64 v8, |v7|, v8, s[0:1]
	v_add_f32_e32 v9, v8, v8
	v_rndne_f32_e32 v9, v9
	v_fmac_f32_e32 v8, -0.5, v9
	v_mul_f32_e32 v11, v8, v8
	v_fmamk_f32 v12, v11, 0x3e75aa41, v220
	v_fmaak_f32 v12, v11, v12, 0x40234736
	v_fmaak_f32 v12, v11, v12, 0xc0a55e0e
	v_mul_f32_e32 v13, v8, v11
	v_mul_f32_e32 v12, v13, v12
	v_cvt_i32_f32_e32 v10, v9
	v_fmac_f32_e32 v12, 0x40490fdb, v8
	v_fmamk_f32 v8, v11, 0x3d4be544, v221
	v_fmaak_f32 v8, v11, v8, 0xbfaad1da
	v_fmaak_f32 v8, v11, v8, 0x4081e0d3
	v_fmaak_f32 v8, v11, v8, 0xc09de9e6
	v_fma_f32 v8, v11, v8, 1.0
	v_and_b32_e32 v11, 1, v10
	v_readlane_b32 s64, v253, 12
	v_readlane_b32 s65, v253, 13
	v_readlane_b32 s66, v253, 14
	v_readlane_b32 s67, v253, 15
	v_lshlrev_b32_e32 v6, 2, v1
	v_cmp_eq_u32_e32 vcc, 0, v11
	v_readlane_b32 s52, v253, 48
	v_ashrrev_i32_e32 v0, 4, v1
	v_and_b32_e32 v2, 60, v6
	v_and_b32_e32 v34, 63, v1
	v_ashrrev_i32_e32 v35, 2, v1
	v_cmp_gt_i32_e64 s[36:37], 64, v1
	v_and_b32_e32 v1, 0x7fffffff, v7
	v_and_b32_e32 v9, 2, v10
	v_cndmask_b32_e64 v11, -v12, v8, vcc
	v_add_u32_e32 v39, s2, v6
	v_cndmask_b32_e32 v6, v8, v12, vcc
	v_lshlrev_b32_e32 v8, 30, v10
	s_lshl_b64 s[22:23], s[28:29], 22
	v_readlane_b32 s60, v253, 56
	v_cmp_eq_u32_e64 s[0:1], 0, v9
	v_and_b32_e32 v8, 0x80000000, v8
	v_xor_b32_e32 v1, v1, v7
	v_readlane_b32 s53, v253, 49
	v_readlane_b32 s61, v253, 57
	s_add_u32 s52, s60, s22
	v_cndmask_b32_e64 v9, -v11, v11, s[0:1]
	s_movk_i32 s0, 0x1f8
	v_xor_b32_e32 v1, v1, v8
	s_addc_u32 s53, s61, s23
	s_lshl_b64 s[34:35], s[28:29], 16
	s_lshl_b64 s[30:31], s[28:29], 10
	v_cmp_class_f32_e64 s[0:1], v7, s0
	v_xor_b32_e32 v1, v1, v6
	v_readlane_b32 s54, v253, 50
	s_add_u32 s29, s52, 0x300000
	v_and_b32_e32 v3, -16, v35
	v_cndmask_b32_e64 v38, v236, v9, s[0:1]
	v_cndmask_b32_e64 v40, v236, v1, s[0:1]
	s_movk_i32 s0, 0x41
	v_readlane_b32 s56, v253, 52
	s_addc_u32 s54, s53, 0
	v_mad_u64_u32 v[10:11], s[0:1], v0, s0, v[2:3]
	v_readlane_b32 s57, v253, 53
	s_add_u32 s0, s56, s34
	v_readlane_b32 s58, v253, 54
	s_addc_u32 s1, s57, s35
	v_readlane_b32 s55, v253, 51
	v_readlane_b32 s59, v253, 55
	s_add_u32 s26, s58, s30
	v_readlane_b32 s66, v253, 62
	s_mul_i32 s55, s28, 0xb00000
	s_addc_u32 s27, s59, s31
	v_readlane_b32 s67, v253, 63
	s_mul_hi_i32 s33, s28, 0xb00000
	s_mul_hi_i32 s60, s28, 0x1600000
	s_mul_i32 s61, s28, 0x1600000
	s_add_u32 s28, s66, s55
	v_readlane_b32 s64, v253, 60
	s_addc_u32 s30, s67, s33
	v_readlane_b32 s65, v253, 61
	s_add_u32 s31, s64, s61
	v_readlane_b32 s62, v253, 58
	v_lshlrev_b32_e32 v184, 1, v34
	v_mov_b32_e32 v36, s2
	v_ashrrev_i32_e32 v1, 31, v0
	v_add_u32_e32 v12, 16, v0
	s_addc_u32 s34, s65, s60
	v_readlane_b32 s63, v253, 59
	v_lshl_add_u64 v[4:5], s[40:41], 0, v[184:185]
	v_lshl_add_u64 v[6:7], s[38:39], 0, v[184:185]
	v_lshl_add_u32 v41, v10, 2, s2
	v_lshlrev_b64 v[10:11], 12, v[0:1]
	v_ashrrev_i32_e32 v13, 31, v12
	v_add_u32_e32 v18, 32, v0
	v_add_u32_e32 v24, 48, v0
	v_lshlrev_b32_e32 v184, 2, v2
	v_mad_u32_u24 v1, v34, s90, v36
	s_add_u32 s22, s62, s22
	v_lshrrev_b32_e32 v34, 4, v35
	v_lshlrev_b32_e32 v8, 6, v0
	v_lshlrev_b32_e32 v14, 6, v12
	v_lshlrev_b64 v[16:17], 12, v[12:13]
	v_lshlrev_b32_e32 v20, 6, v18
	v_ashrrev_i32_e32 v19, 31, v18
	v_lshlrev_b32_e32 v26, 6, v24
	v_ashrrev_i32_e32 v25, 31, v24
	v_lshl_add_u64 v[30:31], s[0:1], 0, v[184:185]
	s_addc_u32 s23, s63, s23
	v_lshlrev_b32_e32 v13, 6, v34
	s_add_i32 s0, s2, 0x4100
	v_ashrrev_i32_e32 v9, 31, v8
	v_ashrrev_i32_e32 v15, 31, v14
	v_ashrrev_i32_e32 v21, 31, v20
	v_lshlrev_b64 v[22:23], 12, v[18:19]
	v_ashrrev_i32_e32 v27, 31, v26
	v_lshlrev_b64 v[28:29], 12, v[24:25]
	v_lshl_add_u64 v[32:33], s[26:27], 0, v[184:185]
	s_movk_i32 s33, 0x3fff
	v_add_u32_e32 v19, s0, v13
	v_lshlrev_b32_e32 v25, 5, v34
	v_mul_lo_u32 v42, v34, 48
	v_readlane_b32 s5, v253, 33
	v_readlane_b32 s6, v253, 34
	v_readlane_b32 s7, v253, 35
	v_readlane_b32 s8, v253, 36
	v_readlane_b32 s9, v253, 37
	v_readlane_b32 s10, v253, 38
	v_readlane_b32 s11, v253, 39
	v_readlane_b32 s12, v253, 40
	v_readlane_b32 s13, v253, 41
	v_readlane_b32 s14, v253, 42
	v_readlane_b32 s15, v253, 43
	v_readlane_b32 s16, v253, 44
	v_readlane_b32 s17, v253, 45
	s_branch .LBB0_153

	.amdhsa_kernel _Z4mega6Paramsiii
		.amdhsa_group_segment_fixed_size 145424
		.amdhsa_private_segment_fixed_size 0
		.amdhsa_kernarg_size 560
		.amdhsa_user_sgpr_count 2
		.amdhsa_user_sgpr_dispatch_ptr 0
		.amdhsa_user_sgpr_queue_ptr 0
		.amdhsa_user_sgpr_kernarg_segment_ptr 1
		.amdhsa_user_sgpr_dispatch_id 0
		.amdhsa_user_sgpr_kernarg_preload_length 0
		.amdhsa_user_sgpr_kernarg_preload_offset 0
		.amdhsa_user_sgpr_private_segment_size 0
		.amdhsa_uses_dynamic_stack 0
		.amdhsa_enable_private_segment 0
		.amdhsa_system_sgpr_workgroup_id_x 1
		.amdhsa_system_sgpr_workgroup_id_y 0
		.amdhsa_system_sgpr_workgroup_id_z 0
		.amdhsa_system_sgpr_workgroup_info 0
		.amdhsa_system_vgpr_workitem_id 2
		.amdhsa_next_free_vgpr 256
		.amdhsa_next_free_sgpr 102
		.amdhsa_accum_offset 256
		.amdhsa_reserve_vcc 1
		.amdhsa_float_round_mode_32 0
		.amdhsa_float_round_mode_16_64 0
		.amdhsa_float_denorm_mode_32 3
		.amdhsa_float_denorm_mode_16_64 3
		.amdhsa_dx10_clamp 1
		.amdhsa_ieee_mode 1
		.amdhsa_fp16_overflow 0
		.amdhsa_tg_split 0
		.amdhsa_exception_fp_ieee_invalid_op 0
		.amdhsa_exception_fp_denorm_src 0
		.amdhsa_exception_fp_ieee_div_zero 0
		.amdhsa_exception_fp_ieee_overflow 0
		.amdhsa_exception_fp_ieee_underflow 0
		.amdhsa_exception_fp_ieee_inexact 0
		.amdhsa_exception_int_div_zero 0
	.end_amdhsa_kernel

amdhsa.kernels:
  - .agpr_count:     0
    .args:
      - .offset:         0
        .size:           288
        .value_kind:     by_value
      - .offset:         288
        .size:           4
        .value_kind:     by_value
      - .offset:         292
        .size:           4
        .value_kind:     by_value
      - .offset:         296
        .size:           4
        .value_kind:     by_value
      - .offset:         304
        .size:           4
        .value_kind:     hidden_block_count_x
      - .offset:         308
        .size:           4
        .value_kind:     hidden_block_count_y
      - .offset:         312
        .size:           4
        .value_kind:     hidden_block_count_z
      - .offset:         316
        .size:           2
        .value_kind:     hidden_group_size_x
      - .offset:         318
        .size:           2
        .value_kind:     hidden_group_size_y
      - .offset:         320
        .size:           2
        .value_kind:     hidden_group_size_z
      - .offset:         322
        .size:           2
        .value_kind:     hidden_remainder_x
      - .offset:         324
        .size:           2
        .value_kind:     hidden_remainder_y
      - .offset:         326
        .size:           2
        .value_kind:     hidden_remainder_z
      - .offset:         344
        .size:           8
        .value_kind:     hidden_global_offset_x
      - .offset:         352
        .size:           8
        .value_kind:     hidden_global_offset_y
      - .offset:         360
        .size:           8
        .value_kind:     hidden_global_offset_z
      - .offset:         368
        .size:           2
        .value_kind:     hidden_grid_dims
      - .offset:         392
        .size:           8
        .value_kind:     hidden_multigrid_sync_arg
    .group_segment_fixed_size: 145424
    .kernarg_segment_align: 8
    .kernarg_segment_size: 560
    .language:       OpenCL C
    .language_version:
      - 2
      - 0
    .max_flat_workgroup_size: 512
    .name:           _Z4mega6Paramsiii
    .private_segment_fixed_size: 0
    .sgpr_count:     108
    .sgpr_spill_count: 202
    .symbol:         _Z4mega6Paramsiii.kd
    .uniform_work_group_size: 1
    .uses_dynamic_stack: false
    .vgpr_count:     256
    .vgpr_spill_count: 0
    .wavefront_size: 64
